# FFN-in: conv weight/bias loads of the epilogue issued before the K loop; epilogue head no longer drains vmcnt
# baseline (speedup 1.0000x reference)
.LBB0_989:
	s_lshl_b32 s6, s30, 7
	v_bfe_i32 v230, v192, 7, 1
	v_and_b32_e32 v230, 0xb00, v230
	v_add_u32_e32 v230, s6, v230
	s_movk_i32 s7, 0x7f
	v_and_or_b32 v230, v192, s7, v230
	v_ashrrev_i32_e32 v231, 31, v230
	v_lshl_add_u64 v[232:233], v[230:231], 2, s[20:21]
	v_ashrrev_i32_e32 v231, 8, v192
	v_mad_i32_i24 v234, v231, s79, v230
	v_ashrrev_i32_e32 v235, 31, v234
	v_lshl_add_u64 v[234:235], v[234:235], 2, s[18:19]
	v_cmp_gt_i32_e32 vcc, 3, v231
	v_add_u32_e32 v231, 0x200, v192
	s_nop 1
	v_cndmask_b32_e32 v235, v233, v235, vcc
	v_cndmask_b32_e32 v234, v232, v234, vcc
	global_load_dword v250, v[234:235], off
	v_ashrrev_i32_e32 v235, 8, v231
	v_mad_i32_i24 v230, v235, s79, v230
	v_ashrrev_i32_e32 v231, 31, v230
	v_lshl_add_u64 v[230:231], v[230:231], 2, s[18:19]
	v_cmp_gt_i32_e32 vcc, 3, v235
	s_nop 1
	v_cndmask_b32_e32 v231, v233, v231, vcc
	v_cndmask_b32_e32 v230, v232, v230, vcc
	global_load_dword v251, v[230:231], off
	s_add_u32 s6, s10, 0x20080
	s_addc_u32 s7, s11, 0
	v_add_u32_e32 v1, s57, v1
	v_add_u32_e32 v134, s63, v0
	s_add_u32 s25, s8, 0x100
	v_mov_b32_e32 v0, 0
	v_mov_b32_e32 v133, v173
	v_mov_b32_e32 v129, v173
	v_mov_b32_e32 v131, v173
	s_addc_u32 s31, s9, 0
	s_mov_b32 s69, -2
	v_add_u32_e32 v135, 0, v1
	v_mov_b32_e32 v1, v0
	v_mov_b32_e32 v2, v0
	v_mov_b32_e32 v3, v0
	v_mov_b32_e32 v8, v0
	v_mov_b32_e32 v9, v0
	v_mov_b32_e32 v10, v0
	v_mov_b32_e32 v11, v0
	v_mov_b32_e32 v16, v0
	v_mov_b32_e32 v17, v0
	v_mov_b32_e32 v18, v0
	v_mov_b32_e32 v19, v0
	v_mov_b32_e32 v20, v0
	v_mov_b32_e32 v21, v0
	v_mov_b32_e32 v22, v0
	v_mov_b32_e32 v23, v0
	v_mov_b32_e32 v32, v0
	v_mov_b32_e32 v33, v0
	v_mov_b32_e32 v34, v0
	v_mov_b32_e32 v35, v0
	v_mov_b32_e32 v36, v0
	v_mov_b32_e32 v37, v0
	v_mov_b32_e32 v38, v0
	v_mov_b32_e32 v39, v0
	v_mov_b32_e32 v48, v0
	v_mov_b32_e32 v49, v0
	v_mov_b32_e32 v50, v0
	v_mov_b32_e32 v51, v0
	v_mov_b32_e32 v52, v0
	v_mov_b32_e32 v53, v0
	v_mov_b32_e32 v54, v0
	v_mov_b32_e32 v55, v0
	v_mov_b32_e32 v12, v0
	v_mov_b32_e32 v13, v0
	v_mov_b32_e32 v14, v0
	v_mov_b32_e32 v15, v0
	v_mov_b32_e32 v4, v0
	v_mov_b32_e32 v5, v0
	v_mov_b32_e32 v6, v0
	v_mov_b32_e32 v7, v0
	v_mov_b32_e32 v24, v0
	v_mov_b32_e32 v25, v0
	v_mov_b32_e32 v26, v0
	v_mov_b32_e32 v27, v0
	v_mov_b32_e32 v28, v0
	v_mov_b32_e32 v29, v0
	v_mov_b32_e32 v30, v0
	v_mov_b32_e32 v31, v0
	v_mov_b32_e32 v40, v0
	v_mov_b32_e32 v41, v0
	v_mov_b32_e32 v42, v0
	v_mov_b32_e32 v43, v0
	v_mov_b32_e32 v44, v0
	v_mov_b32_e32 v45, v0
	v_mov_b32_e32 v46, v0
	v_mov_b32_e32 v47, v0
	v_mov_b32_e32 v56, v0
	v_mov_b32_e32 v57, v0
	v_mov_b32_e32 v58, v0
	v_mov_b32_e32 v59, v0
	v_mov_b32_e32 v60, v0
	v_mov_b32_e32 v61, v0
	v_mov_b32_e32 v62, v0
	v_mov_b32_e32 v63, v0
	v_mov_b32_e32 v64, v0
	v_mov_b32_e32 v65, v0
	v_mov_b32_e32 v66, v0
	v_mov_b32_e32 v67, v0
	v_mov_b32_e32 v68, v0
	v_mov_b32_e32 v69, v0
	v_mov_b32_e32 v70, v0
	v_mov_b32_e32 v71, v0
	v_mov_b32_e32 v80, v0
	v_mov_b32_e32 v81, v0
	v_mov_b32_e32 v82, v0
	v_mov_b32_e32 v83, v0
	v_mov_b32_e32 v84, v0
	v_mov_b32_e32 v85, v0
	v_mov_b32_e32 v86, v0
	v_mov_b32_e32 v87, v0
	v_mov_b32_e32 v96, v0
	v_mov_b32_e32 v97, v0
	v_mov_b32_e32 v98, v0
	v_mov_b32_e32 v99, v0
	v_mov_b32_e32 v100, v0
	v_mov_b32_e32 v101, v0
	v_mov_b32_e32 v102, v0
	v_mov_b32_e32 v103, v0
	v_mov_b32_e32 v112, v0
	v_mov_b32_e32 v113, v0
	v_mov_b32_e32 v114, v0
	v_mov_b32_e32 v115, v0
	v_mov_b32_e32 v116, v0
	v_mov_b32_e32 v117, v0
	v_mov_b32_e32 v118, v0
	v_mov_b32_e32 v119, v0
	v_mov_b32_e32 v72, v0
	v_mov_b32_e32 v73, v0
	v_mov_b32_e32 v74, v0
	v_mov_b32_e32 v75, v0
	v_mov_b32_e32 v76, v0
	v_mov_b32_e32 v77, v0
	v_mov_b32_e32 v78, v0
	v_mov_b32_e32 v79, v0
	v_mov_b32_e32 v88, v0
	v_mov_b32_e32 v89, v0
	v_mov_b32_e32 v90, v0
	v_mov_b32_e32 v91, v0
	v_mov_b32_e32 v92, v0
	v_mov_b32_e32 v93, v0
	v_mov_b32_e32 v94, v0
	v_mov_b32_e32 v95, v0
	v_mov_b32_e32 v104, v0
	v_mov_b32_e32 v105, v0
	v_mov_b32_e32 v106, v0
	v_mov_b32_e32 v107, v0
	v_mov_b32_e32 v108, v0
	v_mov_b32_e32 v109, v0
	v_mov_b32_e32 v110, v0
	v_mov_b32_e32 v111, v0
	v_mov_b32_e32 v120, v0
	v_mov_b32_e32 v121, v0
	v_mov_b32_e32 v122, v0
	v_mov_b32_e32 v123, v0
	v_mov_b32_e32 v124, v0
	v_mov_b32_e32 v125, v0
	v_mov_b32_e32 v126, v0
	v_mov_b32_e32 v127, v0

.LBB0_993:
	v_mov_b32_e32 v134, v192
	v_mov_b32_e32 v135, v192
	s_lshl_b32 s6, s30, 7
	v_bfe_i32 v128, v135, 7, 1
	v_and_b32_e32 v128, 0xb00, v128
	v_add_u32_e32 v128, s6, v128
	s_movk_i32 s7, 0x7f
	v_and_or_b32 v128, v135, s7, v128
	v_ashrrev_i32_e32 v129, 31, v128
	v_lshl_add_u64 v[130:131], v[128:129], 2, s[20:21]
	v_ashrrev_i32_e32 v129, 8, v135
	v_mad_i32_i24 v132, v129, s79, v128
	v_ashrrev_i32_e32 v133, 31, v132
	v_lshl_add_u64 v[132:133], v[132:133], 2, s[18:19]
	v_cmp_gt_i32_e32 vcc, 3, v129
	v_add_u32_e32 v129, 0x200, v135
	v_lshl_add_u32 v135, v135, 2, 0
	v_cndmask_b32_e32 v133, v131, v133, vcc
	v_cndmask_b32_e32 v132, v130, v132, vcc
	v_ashrrev_i32_e32 v133, 8, v129
	v_mad_i32_i24 v128, v133, s79, v128
	v_ashrrev_i32_e32 v129, 31, v128
	v_lshl_add_u64 v[128:129], v[128:129], 2, s[18:19]
	v_cmp_gt_i32_e32 vcc, 3, v133
	s_mulk_i32 s0, 0xfc
	v_lshrrev_b32_e32 v136, 1, v134
	v_cndmask_b32_e32 v129, v131, v129, vcc
	v_cndmask_b32_e32 v128, v130, v128, vcc
	v_add_u32_e32 v135, 0x20000, v135
	s_add_i32 s0, s66, s0
	v_and_b32_e32 v219, 15, v134
	v_and_or_b32 v134, v136, 24, s62
	v_add_u32_e32 v218, s0, v219
	v_or_b32_e32 v136, 0x80, v134
	v_or_b32_e32 v137, 4, v134
	v_or_b32_e32 v138, 0x84, v134
	v_cmp_lt_u32_e32 vcc, 1, v219
	v_or_b32_e32 v188, s6, v134
	v_cmp_gt_i32_e64 s[6:7], s58, v218
	v_lshlrev_b32_e32 v172, 2, v134
	v_lshlrev_b32_e32 v210, 2, v137
	v_lshlrev_b32_e32 v206, 2, v136
	v_lshlrev_b32_e32 v212, 2, v138
	v_ashrrev_i32_e32 v189, 31, v188
	s_and_b64 s[6:7], vcc, s[6:7]
	s_waitcnt vmcnt(8)
	ds_write2st64_b32 v135, v250, v251 offset1:8
	s_waitcnt lgkmcnt(0)
	s_barrier
	v_add_u32_e32 v203, 0x20000, v172
	ds_read_b128 v[128:131], v203 offset:0
	ds_read_b128 v[132:135], v203 offset:512
	ds_read_b128 v[136:139], v203 offset:16
	ds_read_b128 v[140:143], v203 offset:528
	ds_read_b128 v[144:147], v203 offset:1024
	ds_read_b128 v[148:151], v203 offset:1536
	ds_read_b128 v[152:155], v203 offset:1040
	ds_read_b128 v[156:159], v203 offset:1552
	s_waitcnt lgkmcnt(0)
	ds_read_b128 v[160:163], v203 offset:2048
	ds_read_b128 v[164:167], v203 offset:2560
	ds_read_b128 v[168:171], v203 offset:2064
	ds_read_b128 v[204:207], v203 offset:2576
	ds_read_b128 v[208:211], v203 offset:3072
	ds_read_b128 v[212:215], v203 offset:3584
	ds_read_b128 v[220:223], v203 offset:3088
	ds_read_b128 v[224:227], v203 offset:3600
	v_lshl_add_u64 v[190:191], v[188:189], 1, s[16:17]
	s_waitcnt lgkmcnt(0)
	s_add_i32 s6, s0, 2079
	s_mul_hi_u32 s7, s6, s59
	s_lshr_b32 s7, s7, 7
	s_mulk_i32 s7, 0x810
	s_sub_i32 s6, s6, s7
	s_cmp_lt_u32 s6, 17
	s_cbranch_scc1 .Lffn1e_slow0
	v_mov_b32_dpp v228, v124 row_shr:1 row_mask:0xf bank_mask:0xf bound_ctrl:1
	v_mov_b32_dpp v229, v124 row_shr:2 row_mask:0xf bank_mask:0xf bound_ctrl:1
	v_mov_b32_dpp v230, v125 row_shr:1 row_mask:0xf bank_mask:0xf bound_ctrl:1
	v_mov_b32_dpp v231, v125 row_shr:2 row_mask:0xf bank_mask:0xf bound_ctrl:1
	v_mov_b32_dpp v232, v126 row_shr:1 row_mask:0xf bank_mask:0xf bound_ctrl:1
	v_mov_b32_dpp v233, v126 row_shr:2 row_mask:0xf bank_mask:0xf bound_ctrl:1
	v_mov_b32_dpp v234, v127 row_shr:1 row_mask:0xf bank_mask:0xf bound_ctrl:1
	v_mov_b32_dpp v235, v127 row_shr:2 row_mask:0xf bank_mask:0xf bound_ctrl:1
	v_fma_f32 v236, v229, v128, v208
	v_fma_f32 v237, v231, v129, v209
	v_fma_f32 v238, v233, v130, v210
	v_fma_f32 v239, v235, v131, v211
	v_fmac_f32_e32 v236, v228, v144
	v_fmac_f32_e32 v237, v230, v145
	v_fmac_f32_e32 v238, v232, v146
	v_fmac_f32_e32 v239, v234, v147
	v_fmac_f32_e32 v236, v124, v160
	v_fmac_f32_e32 v237, v125, v161
	v_fmac_f32_e32 v238, v126, v162
	v_fmac_f32_e32 v239, v127, v163
	v_mov_b32_dpp v228, v116 row_shr:1 row_mask:0xf bank_mask:0xf bound_ctrl:1
	v_mov_b32_dpp v229, v116 row_shr:2 row_mask:0xf bank_mask:0xf bound_ctrl:1
	v_mov_b32_dpp v230, v117 row_shr:1 row_mask:0xf bank_mask:0xf bound_ctrl:1
	v_mov_b32_dpp v231, v117 row_shr:2 row_mask:0xf bank_mask:0xf bound_ctrl:1
	v_mov_b32_dpp v232, v118 row_shr:1 row_mask:0xf bank_mask:0xf bound_ctrl:1
	v_mov_b32_dpp v233, v118 row_shr:2 row_mask:0xf bank_mask:0xf bound_ctrl:1
	v_mov_b32_dpp v234, v119 row_shr:1 row_mask:0xf bank_mask:0xf bound_ctrl:1
	v_mov_b32_dpp v235, v119 row_shr:2 row_mask:0xf bank_mask:0xf bound_ctrl:1
	v_fma_f32 v240, v229, v132, v212
	v_fma_f32 v241, v231, v133, v213
	v_fma_f32 v242, v233, v134, v214
	v_fma_f32 v243, v235, v135, v215
	v_fmac_f32_e32 v240, v228, v148
	v_fmac_f32_e32 v241, v230, v149
	v_fmac_f32_e32 v242, v232, v150
	v_fmac_f32_e32 v243, v234, v151
	v_fmac_f32_e32 v240, v116, v164
	v_fmac_f32_e32 v241, v117, v165
	v_fmac_f32_e32 v242, v118, v166
	v_fmac_f32_e32 v243, v119, v167
	v_mul_f32_e32 v244, 0x3d372713, v236
	v_mul_f32_e32 v245, 0x3d372713, v237
	v_mul_f32_e32 v246, 0x3d372713, v238
	v_mul_f32_e32 v247, 0x3d372713, v239
	v_mul_f32_e32 v244, v236, v244
	v_mul_f32_e32 v245, v237, v245
	v_mul_f32_e32 v246, v238, v246
	v_mul_f32_e32 v247, v239, v247
	v_fma_f32 v244, v236, v244, v236
	v_fma_f32 v245, v237, v245, v237
	v_fma_f32 v246, v238, v246, v238
	v_fma_f32 v247, v239, v247, v239
	v_mul_f32_e32 v244, 0x3f4c422a, v244
	v_mul_f32_e32 v245, 0x3f4c422a, v245
	v_mul_f32_e32 v246, 0x3f4c422a, v246
	v_mul_f32_e32 v247, 0x3f4c422a, v247
	v_mul_f32_e32 v244, 0xc038aa3b, v244
	v_mul_f32_e32 v245, 0xc038aa3b, v245
	v_mul_f32_e32 v246, 0xc038aa3b, v246
	v_mul_f32_e32 v247, 0xc038aa3b, v247
	v_exp_f32_e32 v244, v244
	v_exp_f32_e32 v245, v245
	v_exp_f32_e32 v246, v246
	v_exp_f32_e32 v247, v247
	v_add_f32_e32 v244, 1.0, v244
	v_add_f32_e32 v245, 1.0, v245
	v_add_f32_e32 v246, 1.0, v246
	v_add_f32_e32 v247, 1.0, v247
	v_rcp_f32_e32 v244, v244
	v_rcp_f32_e32 v245, v245
	v_rcp_f32_e32 v246, v246
	v_rcp_f32_e32 v247, v247
	v_mul_f32_e32 v244, v236, v244
	v_mul_f32_e32 v245, v237, v245
	v_mul_f32_e32 v246, v238, v246
	v_mul_f32_e32 v247, v239, v247
	v_mul_f32_e32 v248, v240, v244
	v_mul_f32_e32 v249, v241, v245
	v_mul_f32_e32 v250, v242, v246
	v_mul_f32_e32 v251, v243, v247
	v_mov_b32_dpp v228, v120 row_shr:1 row_mask:0xf bank_mask:0xf bound_ctrl:1
	v_mov_b32_dpp v229, v120 row_shr:2 row_mask:0xf bank_mask:0xf bound_ctrl:1
	v_mov_b32_dpp v230, v121 row_shr:1 row_mask:0xf bank_mask:0xf bound_ctrl:1
	v_mov_b32_dpp v231, v121 row_shr:2 row_mask:0xf bank_mask:0xf bound_ctrl:1
	v_mov_b32_dpp v232, v122 row_shr:1 row_mask:0xf bank_mask:0xf bound_ctrl:1
	v_mov_b32_dpp v233, v122 row_shr:2 row_mask:0xf bank_mask:0xf bound_ctrl:1
	v_mov_b32_dpp v234, v123 row_shr:1 row_mask:0xf bank_mask:0xf bound_ctrl:1
	v_mov_b32_dpp v235, v123 row_shr:2 row_mask:0xf bank_mask:0xf bound_ctrl:1
	v_fma_f32 v236, v229, v136, v220
	v_fma_f32 v237, v231, v137, v221
	v_fma_f32 v238, v233, v138, v222
	v_fma_f32 v239, v235, v139, v223
	v_fmac_f32_e32 v236, v228, v152
	v_fmac_f32_e32 v237, v230, v153
	v_fmac_f32_e32 v238, v232, v154
	v_fmac_f32_e32 v239, v234, v155
	v_fmac_f32_e32 v236, v120, v168
	v_fmac_f32_e32 v237, v121, v169
	v_fmac_f32_e32 v238, v122, v170
	v_fmac_f32_e32 v239, v123, v171
	v_mov_b32_dpp v228, v112 row_shr:1 row_mask:0xf bank_mask:0xf bound_ctrl:1
	v_mov_b32_dpp v229, v112 row_shr:2 row_mask:0xf bank_mask:0xf bound_ctrl:1
	v_mov_b32_dpp v230, v113 row_shr:1 row_mask:0xf bank_mask:0xf bound_ctrl:1
	v_mov_b32_dpp v231, v113 row_shr:2 row_mask:0xf bank_mask:0xf bound_ctrl:1
	v_mov_b32_dpp v232, v114 row_shr:1 row_mask:0xf bank_mask:0xf bound_ctrl:1
	v_mov_b32_dpp v233, v114 row_shr:2 row_mask:0xf bank_mask:0xf bound_ctrl:1
	v_mov_b32_dpp v234, v115 row_shr:1 row_mask:0xf bank_mask:0xf bound_ctrl:1
	v_mov_b32_dpp v235, v115 row_shr:2 row_mask:0xf bank_mask:0xf bound_ctrl:1
	v_fma_f32 v240, v229, v140, v224
	v_fma_f32 v241, v231, v141, v225
	v_fma_f32 v242, v233, v142, v226
	v_fma_f32 v243, v235, v143, v227
	v_fmac_f32_e32 v240, v228, v156
	v_fmac_f32_e32 v241, v230, v157
	v_fmac_f32_e32 v242, v232, v158
	v_fmac_f32_e32 v243, v234, v159
	v_fmac_f32_e32 v240, v112, v204
	v_fmac_f32_e32 v241, v113, v205
	v_fmac_f32_e32 v242, v114, v206
	v_fmac_f32_e32 v243, v115, v207
	v_mul_f32_e32 v244, 0x3d372713, v236
	v_mul_f32_e32 v245, 0x3d372713, v237
	v_mul_f32_e32 v246, 0x3d372713, v238
	v_mul_f32_e32 v247, 0x3d372713, v239
	v_mul_f32_e32 v244, v236, v244
	v_mul_f32_e32 v245, v237, v245
	v_mul_f32_e32 v246, v238, v246
	v_mul_f32_e32 v247, v239, v247
	v_fma_f32 v244, v236, v244, v236
	v_fma_f32 v245, v237, v245, v237
	v_fma_f32 v246, v238, v246, v238
	v_fma_f32 v247, v239, v247, v239
	v_mul_f32_e32 v244, 0x3f4c422a, v244
	v_mul_f32_e32 v245, 0x3f4c422a, v245
	v_mul_f32_e32 v246, 0x3f4c422a, v246
	v_mul_f32_e32 v247, 0x3f4c422a, v247
	v_mul_f32_e32 v244, 0xc038aa3b, v244
	v_mul_f32_e32 v245, 0xc038aa3b, v245
	v_mul_f32_e32 v246, 0xc038aa3b, v246
	v_mul_f32_e32 v247, 0xc038aa3b, v247
	v_exp_f32_e32 v244, v244
	v_exp_f32_e32 v245, v245
	v_exp_f32_e32 v246, v246
	v_exp_f32_e32 v247, v247
	v_add_f32_e32 v244, 1.0, v244
	v_add_f32_e32 v245, 1.0, v245
	v_add_f32_e32 v246, 1.0, v246
	v_add_f32_e32 v247, 1.0, v247
	v_rcp_f32_e32 v244, v244
	v_rcp_f32_e32 v245, v245
	v_rcp_f32_e32 v246, v246
	v_rcp_f32_e32 v247, v247
	v_mul_f32_e32 v244, v236, v244
	v_mul_f32_e32 v245, v237, v245
	v_mul_f32_e32 v246, v238, v246
	v_mul_f32_e32 v247, v239, v247
	v_mul_f32_e32 v174, v240, v244
	v_mul_f32_e32 v175, v241, v245
	v_mul_f32_e32 v176, v242, v246
	v_mul_f32_e32 v177, v243, v247
	v_cvt_pk_bf16_f32 v180, v248, v249
	v_cvt_pk_bf16_f32 v181, v250, v251
	v_cvt_pk_bf16_f32 v182, v174, v175
	v_cvt_pk_bf16_f32 v183, v176, v177
